# norm phase no longer copies x into the residual buffer: the first residual update reads x straight from the inputs (33 loads redirected, 12 stores dropped)
# baseline (speedup 1.0000x reference)
.LBB0_19:
	s_load_dwordx16 s[12:27], s[0:1], 0x80
	s_lshr_b32 s95, s80, 6
	s_waitcnt lgkmcnt(0)
	s_sub_u32 s98, s36, s30
	s_subb_u32 s99, s37, s31
	s_sub_u32 s98, s98, 0x5200000
	s_subb_u32 s99, s99, 0
	s_sub_u32 s100, s40, s30
	s_subb_u32 s101, s41, s31
	s_sub_u32 s100, s100, 0x9200000
	s_subb_u32 s101, s101, 0
	s_cmp_lt_i32 s90, 1
	s_cselect_b64 s[4:5], -1, 0
	s_cmp_gt_i32 s90, 0
	s_waitcnt lgkmcnt(0)
	v_writelane_b32 v240, s12, 1
	s_cselect_b64 s[0:1], -1, 0
	s_cmp_lt_i32 s91, 1
	v_writelane_b32 v240, s13, 2
	v_writelane_b32 v240, s14, 3
	v_writelane_b32 v240, s15, 4
	v_writelane_b32 v240, s16, 5
	v_writelane_b32 v240, s17, 6
	v_writelane_b32 v240, s18, 7
	v_writelane_b32 v240, s19, 8
	v_writelane_b32 v240, s20, 9
	v_writelane_b32 v240, s21, 10
	v_writelane_b32 v240, s22, 11
	v_writelane_b32 v240, s23, 12
	v_writelane_b32 v240, s24, 13
	s_cselect_b64 s[2:3], -1, 0
	v_writelane_b32 v240, s25, 14
	s_or_b64 s[0:1], s[0:1], s[2:3]
	v_writelane_b32 v240, s26, 15
	v_and_b32_e32 v176, 63, v204
	s_and_b64 vcc, exec, s[0:1]
	v_writelane_b32 v240, s27, 16
	s_cbranch_vccnz .LBB0_50
	v_writelane_b32 v240, s4, 17
	s_cmpk_gt_i32 s8, 0x23f
	s_nop 0
	v_writelane_b32 v240, s5, 18
	s_cbranch_scc1 .LBB0_31
	v_mbcnt_lo_u32_b32 v2, -1, 0
	v_mbcnt_hi_u32_b32 v2, -1, v2
	v_and_b32_e32 v5, 64, v2
	v_xor_b32_e32 v3, 16, v2
	v_add_u32_e32 v5, 64, v5
	v_cmp_lt_i32_e32 vcc, v3, v5
	v_xor_b32_e32 v6, 32, v2
	v_lshlrev_b32_e32 v0, 2, v204
	v_cndmask_b32_e32 v3, v2, v3, vcc
	v_cmp_lt_i32_e32 vcc, v6, v5
	s_and_b32 s0, s80, 0xffffffc0
	v_lshrrev_b32_e32 v4, 4, v176
	v_cndmask_b32_e32 v2, v2, v6, vcc
	v_and_b32_e32 v0, 60, v0
	v_lshlrev_b32_e32 v30, 2, v2
	s_movk_i32 s1, 0xc0
	v_lshrrev_b32_e32 v2, 6, v204
	s_bitcmp1_b32 s8, 0
	v_mov_b32_e32 v1, 0
	v_lshl_add_u32 v6, v0, 2, 0
	v_cmp_gt_u32_e64 s[4:5], s1, v204
	s_mul_i32 s10, s95, 0x300
	v_lshl_add_u32 v7, v176, 2, 0
	v_lshlrev_b32_e32 v8, 8, v2
	v_or_b32_e32 v31, s0, v4
	s_cselect_b64 s[0:1], -1, 0
	s_bitcmp1_b32 s9, 0
	v_lshlrev_b32_e32 v3, 2, v3
	v_cmp_gt_u32_e64 s[2:3], 16, v176
	v_or_b32_e32 v32, 12, v31
	s_cselect_b64 s[6:7], -1, 0
	v_lshlrev_b32_e32 v4, 2, v0
	v_mov_b32_e32 v5, v1
	s_mov_b32 s14, 0x9000
	s_movk_i32 s15, 0x1000
	v_add_u32_e32 v33, s10, v6
	v_add_u32_e32 v34, v7, v8
	v_lshlrev_b32_e32 v0, 2, v176
	s_mov_b32 s16, s97
	s_branch .LBB0_24

.LBB0_107:
	s_or_b64 exec, exec, s[22:23]
	s_cmpk_lt_i32 s20, 0x4000
	s_cselect_b32 s22, s59, 0x4800
	s_cmpk_gt_i32 s20, 0x1fff
	s_cselect_b32 s22, s22, 0
	s_lshl_b32 s22, s22, 2
	s_add_u32 s22, s30, s22
	s_addc_u32 s23, s31, 0
	s_add_u32 s22, s22, 0x1000
	s_addc_u32 s23, s23, 0
	v_lshl_add_u64 v[36:37], v[48:49], 2, s[22:23]
	s_waitcnt lgkmcnt(0)
	global_load_dwordx4 v[32:35], v[50:51], off
	s_lshl_b64 s[24:25], s[20:21], 11
	global_load_dwordx4 v[36:39], v[36:37], off
	s_lshl_b64 s[20:21], s[20:21], 12
	v_lshl_add_u64 v[40:41], v[58:59], 0, s[24:25]
	v_lshl_add_u64 v[42:43], v[60:61], 0, s[20:21]
	s_waitcnt vmcnt(1)
	v_pk_mul_f32 v[34:35], v[14:15], v[34:35]
	v_pk_mul_f32 v[32:33], v[12:13], v[32:33]
	s_waitcnt vmcnt(0)
	v_pk_add_f32 v[38:39], v[38:39], 1.0 op_sel_hi:[1,0]
	v_pk_add_f32 v[36:37], v[36:37], 1.0 op_sel_hi:[1,0]
	v_pk_mul_f32 v[34:35], v[34:35], v[38:39]
	v_pk_mul_f32 v[32:33], v[32:33], v[36:37]
	v_lshl_add_u64 v[36:37], v[52:53], 2, s[22:23]
	v_cvt_pk_f16_f32 v32, v32, v33
	v_cvt_pk_f16_f32 v33, v34, v35
	global_store_dwordx2 v[40:41], v[32:33], off
	global_load_dwordx4 v[32:35], v[50:51], off offset:1024
	s_waitcnt vmcnt(0)
	v_pk_mul_f32 v[34:35], v[10:11], v[34:35]
	global_load_dwordx4 v[36:39], v[36:37], off
	v_pk_mul_f32 v[32:33], v[8:9], v[32:33]
	s_waitcnt vmcnt(0)
	v_pk_add_f32 v[38:39], v[38:39], 1.0 op_sel_hi:[1,0]
	v_pk_add_f32 v[36:37], v[36:37], 1.0 op_sel_hi:[1,0]
	v_pk_mul_f32 v[34:35], v[34:35], v[38:39]
	v_pk_mul_f32 v[32:33], v[32:33], v[36:37]
	v_lshl_add_u64 v[36:37], v[54:55], 2, s[22:23]
	v_cvt_pk_f16_f32 v32, v32, v33
	v_cvt_pk_f16_f32 v33, v34, v35
	global_store_dwordx2 v[40:41], v[32:33], off offset:512
	global_load_dwordx4 v[32:35], v[50:51], off offset:2048
	s_waitcnt vmcnt(0)
	v_pk_mul_f32 v[34:35], v[6:7], v[34:35]
	global_load_dwordx4 v[36:39], v[36:37], off
	v_pk_mul_f32 v[32:33], v[4:5], v[32:33]
	s_waitcnt vmcnt(0)
	v_pk_add_f32 v[38:39], v[38:39], 1.0 op_sel_hi:[1,0]
	v_pk_add_f32 v[36:37], v[36:37], 1.0 op_sel_hi:[1,0]
	v_pk_mul_f32 v[34:35], v[34:35], v[38:39]
	v_pk_mul_f32 v[32:33], v[32:33], v[36:37]
	v_lshl_add_u64 v[36:37], v[56:57], 2, s[22:23]
	v_cvt_pk_f16_f32 v32, v32, v33
	v_cvt_pk_f16_f32 v33, v34, v35
	global_store_dwordx2 v[40:41], v[32:33], off offset:1024
	global_load_dwordx4 v[32:35], v[50:51], off offset:3072
	s_waitcnt vmcnt(0)
	v_pk_mul_f32 v[34:35], v[2:3], v[34:35]
	global_load_dwordx4 v[36:39], v[36:37], off
	v_pk_mul_f32 v[32:33], v[0:1], v[32:33]
	s_waitcnt vmcnt(0)
	v_pk_add_f32 v[38:39], v[38:39], 1.0 op_sel_hi:[1,0]
	v_pk_add_f32 v[36:37], v[36:37], 1.0 op_sel_hi:[1,0]
	v_pk_mul_f32 v[34:35], v[34:35], v[38:39]
	v_pk_mul_f32 v[32:33], v[32:33], v[36:37]
	s_nop 0
	v_cvt_pk_f16_f32 v32, v32, v33
	v_cvt_pk_f16_f32 v33, v34, v35
	global_store_dwordx2 v[40:41], v[32:33], off offset:1536

.LBB0_115:
	s_or_b64 exec, exec, s[34:35]
	s_and_b64 s[26:27], s[26:27], exec
	s_cselect_b32 s26, s59, 0x4800
	s_cmpk_gt_i32 s62, 0x1fff
	s_cselect_b32 s26, s26, 0
	s_lshl_b32 s26, s26, 2
	s_add_u32 s26, s30, s26
	s_addc_u32 s27, s31, 0
	s_add_u32 s26, s26, 0x1000
	s_addc_u32 s27, s27, 0
	v_lshl_add_u64 v[82:83], v[48:49], 2, s[26:27]
	s_waitcnt lgkmcnt(0)
	global_load_dwordx4 v[78:81], v[50:51], off
	v_lshl_add_u64 v[86:87], s[30:31], 0, v[68:69]
	global_load_dwordx4 v[82:85], v[82:83], off
	v_add_co_u32_e32 v86, vcc, s60, v86
	v_lshl_add_u64 v[88:89], s[30:31], 0, v[66:67]
	s_nop 0
	v_addc_co_u32_e32 v87, vcc, 0, v87, vcc
	v_add_co_u32_e32 v88, vcc, s61, v88
	s_waitcnt vmcnt(1)
	v_pk_mul_f32 v[80:81], v[46:47], v[80:81]
	v_pk_mul_f32 v[78:79], v[44:45], v[78:79]
	s_waitcnt vmcnt(0)
	v_pk_add_f32 v[84:85], v[84:85], 1.0 op_sel_hi:[1,0]
	v_pk_add_f32 v[82:83], v[82:83], 1.0 op_sel_hi:[1,0]
	v_pk_mul_f32 v[80:81], v[80:81], v[84:85]
	v_pk_mul_f32 v[78:79], v[78:79], v[82:83]
	v_addc_co_u32_e32 v89, vcc, 0, v89, vcc
	v_cvt_pk_f16_f32 v78, v78, v79
	v_cvt_pk_f16_f32 v79, v80, v81
	global_store_dwordx2 v[86:87], v[78:79], off
	v_lshl_add_u64 v[78:79], v[52:53], 2, s[26:27]
	global_load_dwordx4 v[44:47], v[50:51], off offset:1024
	s_andn2_b64 vcc, exec, s[24:25]
	global_load_dwordx4 v[78:81], v[78:79], off
	s_waitcnt vmcnt(1)
	v_pk_mul_f32 v[46:47], v[42:43], v[46:47]
	v_pk_mul_f32 v[44:45], v[40:41], v[44:45]
	s_waitcnt vmcnt(0)
	v_pk_add_f32 v[80:81], v[80:81], 1.0 op_sel_hi:[1,0]
	v_pk_add_f32 v[78:79], v[78:79], 1.0 op_sel_hi:[1,0]
	v_pk_mul_f32 v[46:47], v[46:47], v[80:81]
	v_pk_mul_f32 v[44:45], v[44:45], v[78:79]
	s_nop 0
	v_cvt_pk_f16_f32 v44, v44, v45
	v_cvt_pk_f16_f32 v45, v46, v47
	global_store_dwordx2 v[86:87], v[44:45], off offset:512
	v_lshl_add_u64 v[44:45], v[54:55], 2, s[26:27]
	global_load_dwordx4 v[40:43], v[50:51], off offset:2048
	s_waitcnt vmcnt(0)
	v_pk_mul_f32 v[42:43], v[38:39], v[42:43]
	global_load_dwordx4 v[44:47], v[44:45], off
	v_pk_mul_f32 v[40:41], v[36:37], v[40:41]
	s_waitcnt vmcnt(0)
	v_pk_add_f32 v[46:47], v[46:47], 1.0 op_sel_hi:[1,0]
	v_pk_add_f32 v[44:45], v[44:45], 1.0 op_sel_hi:[1,0]
	v_pk_mul_f32 v[42:43], v[42:43], v[46:47]
	v_pk_mul_f32 v[40:41], v[40:41], v[44:45]
	s_nop 0
	v_cvt_pk_f16_f32 v40, v40, v41
	v_cvt_pk_f16_f32 v41, v42, v43
	global_store_dwordx2 v[86:87], v[40:41], off offset:1024
	v_lshl_add_u64 v[40:41], v[56:57], 2, s[26:27]
	global_load_dwordx4 v[36:39], v[50:51], off offset:3072
	s_waitcnt vmcnt(0)
	v_pk_mul_f32 v[38:39], v[34:35], v[38:39]
	global_load_dwordx4 v[40:43], v[40:41], off
	v_pk_mul_f32 v[36:37], v[32:33], v[36:37]
	s_waitcnt vmcnt(0)
	v_pk_add_f32 v[42:43], v[42:43], 1.0 op_sel_hi:[1,0]
	v_pk_add_f32 v[40:41], v[40:41], 1.0 op_sel_hi:[1,0]
	v_pk_mul_f32 v[38:39], v[38:39], v[42:43]
	v_pk_mul_f32 v[36:37], v[36:37], v[40:41]
	s_nop 0
	v_cvt_pk_f16_f32 v36, v36, v37
	v_cvt_pk_f16_f32 v37, v38, v39
	global_store_dwordx2 v[86:87], v[36:37], off offset:1536
	s_cbranch_vccnz .LBB0_119
	s_nop 0
	v_mul_f32_e32 v32, v29, v29
	v_mul_f32_e32 v33, v31, v31
	v_fmac_f32_e32 v32, v28, v28
	v_fmac_f32_e32 v33, v30, v30
	v_add_f32_e32 v32, v32, v33
	v_mul_f32_e32 v33, v25, v25
	v_mul_f32_e32 v34, v27, v27
	v_fmac_f32_e32 v33, v24, v24
	v_fmac_f32_e32 v34, v26, v26
	v_add_f32_e32 v33, v33, v34
	v_add_f32_e32 v32, v33, v32
	v_mul_f32_e32 v33, v21, v21
	v_mul_f32_e32 v34, v23, v23
	v_fmac_f32_e32 v33, v20, v20
	v_fmac_f32_e32 v34, v22, v22
	v_add_f32_e32 v33, v33, v34
	v_add_f32_e32 v32, v33, v32
	v_mul_f32_e32 v33, v17, v17
	v_mul_f32_e32 v34, v19, v19
	v_fmac_f32_e32 v33, v16, v16
	v_fmac_f32_e32 v34, v18, v18
	v_add_f32_e32 v33, v33, v34
	v_add_f32_e32 v32, v33, v32
	ds_bpermute_b32 v33, v72, v32
	s_waitcnt lgkmcnt(0)
	v_add_f32_e32 v32, v32, v33
	ds_bpermute_b32 v33, v73, v32
	s_waitcnt lgkmcnt(0)
	v_add_f32_e32 v32, v32, v33
	ds_bpermute_b32 v33, v74, v32
	s_waitcnt lgkmcnt(0)
	v_add_f32_e32 v32, v32, v33
	ds_bpermute_b32 v33, v75, v32
	s_waitcnt lgkmcnt(0)
	v_add_f32_e32 v32, v32, v33
	ds_bpermute_b32 v33, v76, v32
	s_waitcnt lgkmcnt(0)
	v_add_f32_e32 v32, v32, v33
	ds_bpermute_b32 v33, v77, v32
	s_and_saveexec_b64 s[24:25], s[2:3]
	s_cbranch_execz .LBB0_118
	s_add_u32 s26, s30, s49
	s_waitcnt lgkmcnt(0)
	v_add_f32_e32 v32, v32, v33
	s_addc_u32 s27, s31, s56
	global_store_dword v71, v32, s[26:27]
.LBB0_118:
	s_or_b64 exec, exec, s[24:25]
	s_cmpk_lt_i32 s21, 0x4000
	s_cselect_b32 s24, s59, 0x4800
	s_cmpk_gt_i32 s21, 0x1fff
	s_cselect_b32 s21, s24, 0
	s_lshl_b32 s21, s21, 2
	s_add_u32 s21, s30, s21
	s_addc_u32 s25, s31, 0
	s_add_u32 s24, s21, 0x1000
	s_addc_u32 s25, s25, 0
	v_lshl_add_u64 v[36:37], v[48:49], 2, s[24:25]
	s_waitcnt lgkmcnt(0)
	global_load_dwordx4 v[32:35], v[50:51], off
	v_lshl_add_u64 v[40:41], s[30:31], 0, v[64:65]
	global_load_dwordx4 v[36:39], v[36:37], off
	v_add_co_u32_e32 v40, vcc, s60, v40
	v_lshl_add_u64 v[42:43], s[30:31], 0, v[62:63]
	s_nop 0
	v_addc_co_u32_e32 v41, vcc, 0, v41, vcc
	v_add_co_u32_e32 v42, vcc, s61, v42
	s_waitcnt vmcnt(1)
	v_pk_mul_f32 v[34:35], v[30:31], v[34:35]
	v_pk_mul_f32 v[32:33], v[28:29], v[32:33]
	s_waitcnt vmcnt(0)
	v_pk_add_f32 v[38:39], v[38:39], 1.0 op_sel_hi:[1,0]
	v_pk_add_f32 v[36:37], v[36:37], 1.0 op_sel_hi:[1,0]
	v_pk_mul_f32 v[34:35], v[34:35], v[38:39]
	v_pk_mul_f32 v[32:33], v[32:33], v[36:37]
	v_addc_co_u32_e32 v43, vcc, 0, v43, vcc
	v_cvt_pk_f16_f32 v32, v32, v33
	v_cvt_pk_f16_f32 v33, v34, v35
	global_store_dwordx2 v[40:41], v[32:33], off
	v_lshl_add_u64 v[36:37], v[52:53], 2, s[24:25]
	global_load_dwordx4 v[32:35], v[50:51], off offset:1024
	s_waitcnt vmcnt(0)
	v_pk_mul_f32 v[34:35], v[26:27], v[34:35]
	global_load_dwordx4 v[36:39], v[36:37], off
	v_pk_mul_f32 v[32:33], v[24:25], v[32:33]
	s_waitcnt vmcnt(0)
	v_pk_add_f32 v[38:39], v[38:39], 1.0 op_sel_hi:[1,0]
	v_pk_add_f32 v[36:37], v[36:37], 1.0 op_sel_hi:[1,0]
	v_pk_mul_f32 v[34:35], v[34:35], v[38:39]
	v_pk_mul_f32 v[32:33], v[32:33], v[36:37]
	v_lshl_add_u64 v[36:37], v[54:55], 2, s[24:25]
	v_cvt_pk_f16_f32 v32, v32, v33
	v_cvt_pk_f16_f32 v33, v34, v35
	global_store_dwordx2 v[40:41], v[32:33], off offset:512
	global_load_dwordx4 v[32:35], v[50:51], off offset:2048
	s_waitcnt vmcnt(0)
	v_pk_mul_f32 v[34:35], v[22:23], v[34:35]
	global_load_dwordx4 v[36:39], v[36:37], off
	v_pk_mul_f32 v[32:33], v[20:21], v[32:33]
	s_waitcnt vmcnt(0)
	v_pk_add_f32 v[38:39], v[38:39], 1.0 op_sel_hi:[1,0]
	v_pk_add_f32 v[36:37], v[36:37], 1.0 op_sel_hi:[1,0]
	v_pk_mul_f32 v[34:35], v[34:35], v[38:39]
	v_pk_mul_f32 v[32:33], v[32:33], v[36:37]
	v_lshl_add_u64 v[36:37], v[56:57], 2, s[24:25]
	v_cvt_pk_f16_f32 v32, v32, v33
	v_cvt_pk_f16_f32 v33, v34, v35
	global_store_dwordx2 v[40:41], v[32:33], off offset:1024
	global_load_dwordx4 v[32:35], v[50:51], off offset:3072
	s_waitcnt vmcnt(0)
	v_pk_mul_f32 v[34:35], v[18:19], v[34:35]
	global_load_dwordx4 v[36:39], v[36:37], off
	v_pk_mul_f32 v[32:33], v[16:17], v[32:33]
	s_waitcnt vmcnt(0)
	v_pk_add_f32 v[38:39], v[38:39], 1.0 op_sel_hi:[1,0]
	v_pk_add_f32 v[36:37], v[36:37], 1.0 op_sel_hi:[1,0]
	v_pk_mul_f32 v[34:35], v[34:35], v[38:39]
	v_pk_mul_f32 v[32:33], v[32:33], v[36:37]
	s_nop 0
	v_cvt_pk_f16_f32 v32, v32, v33
	v_cvt_pk_f16_f32 v33, v34, v35
	global_store_dwordx2 v[40:41], v[32:33], off offset:1536

.LBB0_344:
	s_cmp_lt_i32 s63, 64
	s_cselect_b32 s22, 1, 2
	s_cmp_gt_i32 s63, 31
	s_cselect_b32 s24, s22, 0
	s_mul_i32 s22, s24, 0x9000
	v_lshl_or_b32 v178, s64, 8, v207
	s_add_u32 s22, s47, s22
	v_ashrrev_i32_e32 v179, 31, v178
	s_addc_u32 s23, s48, 0
	v_lshlrev_b64 v[80:81], 2, v[178:179]
	v_lshl_add_u64 v[82:83], s[22:23], 0, v[80:81]
	v_lshl_add_u32 v196, s63, 8, v177
	global_load_dwordx4 v[180:183], v[82:83], off offset:16
	global_load_dwordx4 v[184:187], v[82:83], off
	v_ashrrev_i32_e32 v197, 31, v196
	global_load_dwordx4 v[212:215], v[82:83], off offset:528
	global_load_dwordx4 v[216:219], v[82:83], off offset:512
	v_lshl_add_u64 v[198:199], s[38:39], 0, v[80:81]
	v_lshlrev_b64 v[82:83], 12, v[196:197]
	s_lshl_b32 s22, s24, 12
	v_lshl_add_u64 v[236:237], v[198:199], 0, v[82:83]
	s_add_u32 s22, s49, s22
	v_lshl_add_u64 v[242:243], s[98:99], 0, v[236:237]
	global_load_dwordx4 v[220:223], v[242:243], off
	v_lshl_add_u64 v[242:243], s[98:99], 0, v[236:237]
	global_load_dwordx4 v[224:227], v[242:243], off offset:16
	v_lshl_add_u64 v[242:243], s[98:99], 0, v[236:237]
	global_load_dwordx4 v[228:231], v[242:243], off offset:512
	v_lshl_add_u64 v[242:243], s[98:99], 0, v[236:237]
	global_load_dwordx4 v[232:235], v[242:243], off offset:528
	s_addc_u32 s23, s54, 0
	v_lshl_add_u64 v[80:81], s[22:23], 0, v[80:81]
	global_load_dwordx4 v[96:99], v[80:81], off
	global_load_dwordx4 v[92:95], v[80:81], off offset:16
	global_load_dwordx4 v[84:87], v[80:81], off offset:512
	s_nop 0
	global_load_dwordx4 v[80:83], v[80:81], off offset:528
	v_or_b32_e32 v200, 16, v196
	v_ashrrev_i32_e32 v201, 31, v200
	v_lshlrev_b64 v[144:145], 12, v[200:201]
	v_lshl_add_u64 v[202:203], v[198:199], 0, v[144:145]
	v_lshl_add_u64 v[242:243], s[98:99], 0, v[202:203]
	global_load_dwordx4 v[152:155], v[242:243], off offset:16
	v_lshl_add_u64 v[242:243], s[98:99], 0, v[202:203]
	global_load_dwordx4 v[156:159], v[242:243], off
	v_lshl_add_u64 v[242:243], s[98:99], 0, v[202:203]
	global_load_dwordx4 v[144:147], v[242:243], off offset:528
	v_lshl_add_u64 v[242:243], s[98:99], 0, v[202:203]
	global_load_dwordx4 v[148:151], v[242:243], off offset:512
	v_lshlrev_b64 v[188:189], 10, v[196:197]
	v_lshl_add_u64 v[188:189], v[188:189], 0, v[178:179]
	v_lshl_add_u64 v[238:239], v[188:189], 1, s[42:43]
	s_waitcnt vmcnt(0)
	v_pk_mul_f32 v[190:191], v[182:183], 0.5 op_sel_hi:[1,0]
	v_pk_mul_f32 v[192:193], v[186:187], 0.5 op_sel_hi:[1,0]
	v_pk_mul_f32 v[194:195], v[184:185], 0.5 op_sel_hi:[1,0]
	v_pk_mul_f32 v[188:189], v[180:181], 0.5 op_sel_hi:[1,0]
	v_pk_mul_f32 v[184:185], v[218:219], 0.5 op_sel_hi:[1,0]
	v_pk_mul_f32 v[186:187], v[216:217], 0.5 op_sel_hi:[1,0]
	v_pk_fma_f32 v[142:143], v[142:143], v[192:193], v[222:223]
	v_pk_fma_f32 v[140:141], v[140:141], v[194:195], v[220:221]
	v_pk_fma_f32 v[138:139], v[138:139], v[190:191], v[226:227]
	v_pk_fma_f32 v[136:137], v[136:137], v[188:189], v[224:225]
	v_pk_mul_f32 v[182:183], v[214:215], 0.5 op_sel_hi:[1,0]
	v_pk_mul_f32 v[180:181], v[212:213], 0.5 op_sel_hi:[1,0]
	v_pk_fma_f32 v[134:135], v[134:135], v[184:185], v[230:231]
	v_pk_fma_f32 v[132:133], v[132:133], v[186:187], v[228:229]
	v_mul_f32_e32 v220, v141, v141
	v_mul_f32_e32 v221, v142, v142
	v_mul_f32_e32 v222, v137, v137
	v_mul_f32_e32 v223, v138, v138
	v_pk_fma_f32 v[130:131], v[130:131], v[182:183], v[234:235]
	v_pk_fma_f32 v[128:129], v[128:129], v[180:181], v[232:233]
	global_store_dwordx4 v[236:237], v[140:143], off
	v_pk_mul_f32 v[212:213], v[98:99], v[142:143]
	v_pk_mul_f32 v[214:215], v[96:97], v[140:141]
	v_pk_mul_f32 v[216:217], v[94:95], v[138:139]
	v_pk_mul_f32 v[218:219], v[92:93], v[136:137]
	v_mul_f32_e32 v141, v133, v133
	v_mul_f32_e32 v142, v134, v134
	v_fmac_f32_e32 v220, v140, v140
	v_fmac_f32_e32 v221, v143, v143
	v_fmac_f32_e32 v222, v136, v136
	v_fmac_f32_e32 v223, v139, v139
	global_store_dwordx4 v[236:237], v[136:139], off offset:16
	v_mul_f32_e32 v224, v129, v129
	v_mul_f32_e32 v225, v130, v130
	v_cvt_pk_f16_f32 v136, v214, v215
	v_cvt_pk_f16_f32 v137, v212, v213
	v_cvt_pk_f16_f32 v138, v218, v219
	v_cvt_pk_f16_f32 v139, v216, v217
	v_fmac_f32_e32 v141, v132, v132
	v_fmac_f32_e32 v142, v135, v135
	v_add_f32_e32 v140, v220, v221
	v_add_f32_e32 v143, v222, v223
	v_fmac_f32_e32 v224, v128, v128
	v_fmac_f32_e32 v225, v131, v131
	global_store_dwordx4 v[238:239], v[136:139], off
	global_store_dwordx4 v[236:237], v[132:135], off offset:512
	global_store_dwordx4 v[236:237], v[128:131], off offset:528
	v_add_f32_e32 v136, v141, v142
	v_add_f32_e32 v137, v140, v143
	v_add_f32_e32 v136, v137, v136
	v_add_f32_e32 v137, v224, v225
	v_add_f32_e32 v142, v136, v137
	v_pk_mul_f32 v[136:137], v[86:87], v[134:135]
	v_and_b32_e32 v135, 64, v211
	v_xor_b32_e32 v134, 16, v211
	v_add_u32_e32 v135, 64, v135
	v_cmp_lt_i32_e32 vcc, v134, v135
	v_pk_mul_f32 v[140:141], v[80:81], v[128:129]
	v_xor_b32_e32 v129, 32, v211
	v_cndmask_b32_e32 v134, v211, v134, vcc
	v_lshlrev_b32_e32 v134, 2, v134
	ds_bpermute_b32 v143, v134, v142
	v_cmp_lt_i32_e32 vcc, v129, v135
	v_pk_mul_f32 v[132:133], v[84:85], v[132:133]
	v_pk_mul_f32 v[138:139], v[82:83], v[130:131]
	v_cndmask_b32_e32 v129, v211, v129, vcc
	s_waitcnt lgkmcnt(0)
	v_add_f32_e32 v128, v142, v143
	v_lshlrev_b32_e32 v135, 2, v129
	ds_bpermute_b32 v129, v135, v128
	v_cvt_pk_f16_f32 v130, v132, v133
	v_cvt_pk_f16_f32 v131, v136, v137
	v_cvt_pk_f16_f32 v132, v140, v141
	v_cvt_pk_f16_f32 v133, v138, v139
	global_store_dwordx4 v[238:239], v[130:133], off offset:256
	s_and_saveexec_b64 s[22:23], s[2:3]
	s_cbranch_execz .LBB0_346
	v_lshl_add_u64 v[130:131], v[196:197], 2, s[12:13]
	s_waitcnt lgkmcnt(0)
	v_add_f32_e32 v128, v128, v129
	global_atomic_add_f32 v[130:131], v128, off

.LBB0_348:
	s_or_b64 exec, exec, s[22:23]
	v_or_b32_e32 v132, 32, v196
	v_ashrrev_i32_e32 v133, 31, v132
	s_waitcnt lgkmcnt(0)
	v_lshlrev_b64 v[112:113], 12, v[132:133]
	v_lshl_add_u64 v[152:153], v[198:199], 0, v[112:113]
	v_lshl_add_u64 v[242:243], s[98:99], 0, v[152:153]
	global_load_dwordx4 v[136:139], v[242:243], off
	v_lshl_add_u64 v[242:243], s[98:99], 0, v[152:153]
	global_load_dwordx4 v[140:143], v[242:243], off offset:16
	v_lshl_add_u64 v[242:243], s[98:99], 0, v[152:153]
	global_load_dwordx4 v[144:147], v[242:243], off offset:512
	v_lshl_add_u64 v[242:243], s[98:99], 0, v[152:153]
	global_load_dwordx4 v[148:151], v[242:243], off offset:528
	v_or_b32_e32 v128, 48, v196
	v_ashrrev_i32_e32 v129, 31, v128
	v_lshlrev_b64 v[112:113], 12, v[128:129]
	v_lshl_add_u64 v[130:131], v[198:199], 0, v[112:113]
	v_lshl_add_u64 v[242:243], s[98:99], 0, v[130:131]
	global_load_dwordx4 v[120:123], v[242:243], off offset:16
	v_lshl_add_u64 v[242:243], s[98:99], 0, v[130:131]
	global_load_dwordx4 v[124:127], v[242:243], off
	v_lshl_add_u64 v[242:243], s[98:99], 0, v[130:131]
	global_load_dwordx4 v[112:115], v[242:243], off offset:528
	v_lshl_add_u64 v[242:243], s[98:99], 0, v[130:131]
	global_load_dwordx4 v[116:119], v[242:243], off offset:512
	v_lshlrev_b64 v[154:155], 10, v[132:133]
	v_lshl_add_u64 v[154:155], v[154:155], 0, v[178:179]
	v_lshl_add_u64 v[154:155], v[154:155], 1, s[42:43]
	s_waitcnt vmcnt(7)
	v_pk_fma_f32 v[110:111], v[110:111], v[192:193], v[138:139]
	v_pk_fma_f32 v[108:109], v[108:109], v[194:195], v[136:137]
	s_waitcnt vmcnt(6)
	v_pk_fma_f32 v[106:107], v[106:107], v[190:191], v[142:143]
	v_pk_fma_f32 v[104:105], v[104:105], v[188:189], v[140:141]
	s_waitcnt vmcnt(5)
	v_pk_fma_f32 v[102:103], v[102:103], v[184:185], v[146:147]
	v_pk_fma_f32 v[100:101], v[100:101], v[186:187], v[144:145]
	v_mul_f32_e32 v144, v109, v109
	v_mul_f32_e32 v145, v110, v110
	v_mul_f32_e32 v146, v105, v105
	v_mul_f32_e32 v147, v106, v106
	s_waitcnt vmcnt(4)
	v_pk_fma_f32 v[90:91], v[90:91], v[182:183], v[150:151]
	v_pk_fma_f32 v[88:89], v[88:89], v[180:181], v[148:149]
	global_store_dwordx4 v[152:153], v[108:111], off
	v_pk_mul_f32 v[136:137], v[98:99], v[110:111]
	v_pk_mul_f32 v[138:139], v[96:97], v[108:109]
	v_pk_mul_f32 v[140:141], v[94:95], v[106:107]
	v_pk_mul_f32 v[142:143], v[92:93], v[104:105]
	v_mul_f32_e32 v109, v101, v101
	v_mul_f32_e32 v110, v102, v102
	v_fmac_f32_e32 v144, v108, v108
	v_fmac_f32_e32 v145, v111, v111
	v_fmac_f32_e32 v146, v104, v104
	v_fmac_f32_e32 v147, v107, v107
	global_store_dwordx4 v[152:153], v[104:107], off offset:16
	v_mul_f32_e32 v148, v89, v89
	v_mul_f32_e32 v149, v90, v90
	v_cvt_pk_f16_f32 v104, v138, v139
	v_cvt_pk_f16_f32 v105, v136, v137
	v_cvt_pk_f16_f32 v106, v142, v143
	v_cvt_pk_f16_f32 v107, v140, v141
	v_fmac_f32_e32 v109, v100, v100
	v_fmac_f32_e32 v110, v103, v103
	v_add_f32_e32 v108, v144, v145
	v_add_f32_e32 v111, v146, v147
	v_fmac_f32_e32 v148, v88, v88
	v_fmac_f32_e32 v149, v91, v91
	global_store_dwordx4 v[154:155], v[104:107], off
	global_store_dwordx4 v[152:153], v[100:103], off offset:512
	global_store_dwordx4 v[152:153], v[88:91], off offset:528
	v_add_f32_e32 v104, v109, v110
	v_add_f32_e32 v106, v108, v111
	v_add_f32_e32 v105, v148, v149
	v_add_f32_e32 v104, v106, v104
	v_add_f32_e32 v106, v104, v105
	ds_bpermute_b32 v107, v134, v106
	v_pk_mul_f32 v[104:105], v[80:81], v[88:89]
	v_pk_mul_f32 v[102:103], v[86:87], v[102:103]
	v_pk_mul_f32 v[100:101], v[84:85], v[100:101]
	v_pk_mul_f32 v[90:91], v[82:83], v[90:91]
	s_waitcnt lgkmcnt(0)
	v_add_f32_e32 v88, v106, v107
	ds_bpermute_b32 v89, v135, v88
	v_cvt_pk_f16_f32 v100, v100, v101
	v_cvt_pk_f16_f32 v101, v102, v103
	v_cvt_pk_f16_f32 v102, v104, v105
	v_cvt_pk_f16_f32 v103, v90, v91
	global_store_dwordx4 v[154:155], v[100:103], off offset:256
	s_and_saveexec_b64 s[22:23], s[2:3]
	s_cbranch_execz .LBB0_350
	v_lshl_add_u64 v[90:91], v[132:133], 2, s[12:13]
	s_waitcnt lgkmcnt(0)
	v_add_f32_e32 v88, v88, v89
	global_atomic_add_f32 v[90:91], v88, off

.LBB0_352:
	s_or_b64 exec, exec, s[22:23]
	v_add_u32_e32 v100, 0x80, v196
	v_ashrrev_i32_e32 v101, 31, v100
	s_waitcnt lgkmcnt(0)
	v_lshlrev_b64 v[64:65], 12, v[100:101]
	v_lshl_add_u64 v[118:119], v[198:199], 0, v[64:65]
	v_lshl_add_u64 v[242:243], s[98:99], 0, v[118:119]
	global_load_dwordx4 v[102:105], v[242:243], off
	v_lshl_add_u64 v[242:243], s[98:99], 0, v[118:119]
	global_load_dwordx4 v[106:109], v[242:243], off offset:16
	v_lshl_add_u64 v[242:243], s[98:99], 0, v[118:119]
	global_load_dwordx4 v[110:113], v[242:243], off offset:512
	v_lshl_add_u64 v[242:243], s[98:99], 0, v[118:119]
	global_load_dwordx4 v[114:117], v[242:243], off offset:528
	v_add_u32_e32 v88, 0x90, v196
	v_ashrrev_i32_e32 v89, 31, v88
	v_lshlrev_b64 v[64:65], 12, v[88:89]
	v_lshl_add_u64 v[90:91], v[198:199], 0, v[64:65]
	v_lshl_add_u64 v[242:243], s[98:99], 0, v[90:91]
	global_load_dwordx4 v[72:75], v[242:243], off offset:16
	v_lshl_add_u64 v[242:243], s[98:99], 0, v[90:91]
	global_load_dwordx4 v[76:79], v[242:243], off
	v_lshl_add_u64 v[242:243], s[98:99], 0, v[90:91]
	global_load_dwordx4 v[64:67], v[242:243], off offset:528
	v_lshl_add_u64 v[242:243], s[98:99], 0, v[90:91]
	global_load_dwordx4 v[68:71], v[242:243], off offset:512
	v_lshlrev_b64 v[120:121], 10, v[100:101]
	v_lshl_add_u64 v[120:121], v[120:121], 0, v[178:179]
	v_lshl_add_u64 v[120:121], v[120:121], 1, s[42:43]
	s_waitcnt vmcnt(7)
	v_pk_fma_f32 v[62:63], v[62:63], v[192:193], v[104:105]
	v_pk_fma_f32 v[60:61], v[60:61], v[194:195], v[102:103]
	s_waitcnt vmcnt(6)
	v_pk_fma_f32 v[58:59], v[58:59], v[190:191], v[108:109]
	v_pk_fma_f32 v[56:57], v[56:57], v[188:189], v[106:107]
	s_waitcnt vmcnt(5)
	v_pk_fma_f32 v[54:55], v[54:55], v[184:185], v[112:113]
	v_pk_fma_f32 v[52:53], v[52:53], v[186:187], v[110:111]
	v_mul_f32_e32 v110, v61, v61
	v_mul_f32_e32 v111, v62, v62
	v_mul_f32_e32 v112, v57, v57
	v_mul_f32_e32 v113, v58, v58
	s_waitcnt vmcnt(4)
	v_pk_fma_f32 v[50:51], v[50:51], v[182:183], v[116:117]
	v_pk_fma_f32 v[48:49], v[48:49], v[180:181], v[114:115]
	global_store_dwordx4 v[118:119], v[60:63], off
	v_pk_mul_f32 v[102:103], v[98:99], v[62:63]
	v_pk_mul_f32 v[104:105], v[96:97], v[60:61]
	v_pk_mul_f32 v[106:107], v[94:95], v[58:59]
	v_pk_mul_f32 v[108:109], v[92:93], v[56:57]
	v_mul_f32_e32 v61, v53, v53
	v_mul_f32_e32 v62, v54, v54
	v_fmac_f32_e32 v110, v60, v60
	v_fmac_f32_e32 v111, v63, v63
	v_fmac_f32_e32 v112, v56, v56
	v_fmac_f32_e32 v113, v59, v59
	global_store_dwordx4 v[118:119], v[56:59], off offset:16
	v_mul_f32_e32 v114, v49, v49
	v_mul_f32_e32 v115, v50, v50
	v_cvt_pk_f16_f32 v56, v104, v105
	v_cvt_pk_f16_f32 v57, v102, v103
	v_cvt_pk_f16_f32 v58, v108, v109
	v_cvt_pk_f16_f32 v59, v106, v107
	v_fmac_f32_e32 v61, v52, v52
	v_fmac_f32_e32 v62, v55, v55
	v_add_f32_e32 v60, v110, v111
	v_add_f32_e32 v63, v112, v113
	v_fmac_f32_e32 v114, v48, v48
	v_fmac_f32_e32 v115, v51, v51
	global_store_dwordx4 v[120:121], v[56:59], off
	global_store_dwordx4 v[118:119], v[52:55], off offset:512
	global_store_dwordx4 v[118:119], v[48:51], off offset:528
	v_add_f32_e32 v56, v61, v62
	v_add_f32_e32 v58, v60, v63
	v_add_f32_e32 v57, v114, v115
	v_add_f32_e32 v56, v58, v56
	v_add_f32_e32 v60, v56, v57
	ds_bpermute_b32 v61, v134, v60
	v_pk_mul_f32 v[58:59], v[80:81], v[48:49]
	v_pk_mul_f32 v[54:55], v[86:87], v[54:55]
	v_pk_mul_f32 v[52:53], v[84:85], v[52:53]
	v_pk_mul_f32 v[56:57], v[82:83], v[50:51]
	s_waitcnt lgkmcnt(0)
	v_add_f32_e32 v48, v60, v61
	ds_bpermute_b32 v49, v135, v48
	v_cvt_pk_f16_f32 v50, v52, v53
	v_cvt_pk_f16_f32 v51, v54, v55
	v_cvt_pk_f16_f32 v52, v58, v59
	v_cvt_pk_f16_f32 v53, v56, v57
	global_store_dwordx4 v[120:121], v[50:53], off offset:256
	s_and_saveexec_b64 s[22:23], s[2:3]
	s_cbranch_execz .LBB0_354
	v_lshl_add_u64 v[50:51], v[100:101], 2, s[12:13]
	s_waitcnt lgkmcnt(0)
	v_add_f32_e32 v48, v48, v49
	global_atomic_add_f32 v[50:51], v48, off

.LBB0_356:
	s_or_b64 exec, exec, s[22:23]
	v_add_u32_e32 v52, 0xa0, v196
	v_ashrrev_i32_e32 v53, 31, v52
	s_waitcnt lgkmcnt(0)
	v_lshlrev_b64 v[32:33], 12, v[52:53]
	v_lshl_add_u64 v[70:71], v[198:199], 0, v[32:33]
	v_lshl_add_u64 v[242:243], s[98:99], 0, v[70:71]
	global_load_dwordx4 v[54:57], v[242:243], off
	v_lshl_add_u64 v[242:243], s[98:99], 0, v[70:71]
	global_load_dwordx4 v[58:61], v[242:243], off offset:16
	v_lshl_add_u64 v[242:243], s[98:99], 0, v[70:71]
	global_load_dwordx4 v[62:65], v[242:243], off offset:512
	v_lshl_add_u64 v[242:243], s[98:99], 0, v[70:71]
	global_load_dwordx4 v[66:69], v[242:243], off offset:528
	v_add_u32_e32 v48, 0xb0, v196
	v_ashrrev_i32_e32 v49, 31, v48
	v_lshlrev_b64 v[32:33], 12, v[48:49]
	v_lshl_add_u64 v[50:51], v[198:199], 0, v[32:33]
	v_lshl_add_u64 v[242:243], s[98:99], 0, v[50:51]
	global_load_dwordx4 v[40:43], v[242:243], off offset:16
	v_lshl_add_u64 v[242:243], s[98:99], 0, v[50:51]
	global_load_dwordx4 v[44:47], v[242:243], off
	v_lshl_add_u64 v[242:243], s[98:99], 0, v[50:51]
	global_load_dwordx4 v[32:35], v[242:243], off offset:528
	v_lshl_add_u64 v[242:243], s[98:99], 0, v[50:51]
	global_load_dwordx4 v[36:39], v[242:243], off offset:512
	v_lshlrev_b64 v[72:73], 10, v[52:53]
	v_lshl_add_u64 v[72:73], v[72:73], 0, v[178:179]
	v_lshl_add_u64 v[72:73], v[72:73], 1, s[42:43]
	s_waitcnt vmcnt(7)
	v_pk_fma_f32 v[30:31], v[30:31], v[192:193], v[56:57]
	v_pk_fma_f32 v[28:29], v[28:29], v[194:195], v[54:55]
	s_waitcnt vmcnt(6)
	v_pk_fma_f32 v[26:27], v[26:27], v[190:191], v[60:61]
	v_pk_fma_f32 v[24:25], v[24:25], v[188:189], v[58:59]
	s_waitcnt vmcnt(5)
	v_pk_fma_f32 v[22:23], v[22:23], v[184:185], v[64:65]
	v_pk_fma_f32 v[20:21], v[20:21], v[186:187], v[62:63]
	v_mul_f32_e32 v62, v29, v29
	v_mul_f32_e32 v63, v30, v30
	v_mul_f32_e32 v64, v25, v25
	v_mul_f32_e32 v65, v26, v26
	s_waitcnt vmcnt(4)
	v_pk_fma_f32 v[18:19], v[18:19], v[182:183], v[68:69]
	v_pk_fma_f32 v[16:17], v[16:17], v[180:181], v[66:67]
	global_store_dwordx4 v[70:71], v[28:31], off
	v_pk_mul_f32 v[54:55], v[98:99], v[30:31]
	v_pk_mul_f32 v[56:57], v[96:97], v[28:29]
	v_pk_mul_f32 v[58:59], v[94:95], v[26:27]
	v_pk_mul_f32 v[60:61], v[92:93], v[24:25]
	v_mul_f32_e32 v29, v21, v21
	v_mul_f32_e32 v30, v22, v22
	v_fmac_f32_e32 v62, v28, v28
	v_fmac_f32_e32 v63, v31, v31
	v_fmac_f32_e32 v64, v24, v24
	v_fmac_f32_e32 v65, v27, v27
	global_store_dwordx4 v[70:71], v[24:27], off offset:16
	v_mul_f32_e32 v66, v17, v17
	v_mul_f32_e32 v67, v18, v18
	v_cvt_pk_f16_f32 v24, v56, v57
	v_cvt_pk_f16_f32 v25, v54, v55
	v_cvt_pk_f16_f32 v26, v60, v61
	v_cvt_pk_f16_f32 v27, v58, v59
	v_fmac_f32_e32 v29, v20, v20
	v_fmac_f32_e32 v30, v23, v23
	v_add_f32_e32 v28, v62, v63
	v_add_f32_e32 v31, v64, v65
	v_fmac_f32_e32 v66, v16, v16
	v_fmac_f32_e32 v67, v19, v19
	global_store_dwordx4 v[72:73], v[24:27], off
	global_store_dwordx4 v[70:71], v[20:23], off offset:512
	global_store_dwordx4 v[70:71], v[16:19], off offset:528
	v_add_f32_e32 v24, v29, v30
	v_add_f32_e32 v26, v28, v31
	v_add_f32_e32 v25, v66, v67
	v_add_f32_e32 v24, v26, v24
	v_add_f32_e32 v28, v24, v25
	ds_bpermute_b32 v29, v134, v28
	v_pk_mul_f32 v[26:27], v[80:81], v[16:17]
	v_pk_mul_f32 v[22:23], v[86:87], v[22:23]
	v_pk_mul_f32 v[20:21], v[84:85], v[20:21]
	v_pk_mul_f32 v[24:25], v[82:83], v[18:19]
	s_waitcnt lgkmcnt(0)
	v_add_f32_e32 v16, v28, v29
	ds_bpermute_b32 v17, v135, v16
	v_cvt_pk_f16_f32 v18, v20, v21
	v_cvt_pk_f16_f32 v19, v22, v23
	v_cvt_pk_f16_f32 v20, v26, v27
	v_cvt_pk_f16_f32 v21, v24, v25
	global_store_dwordx4 v[72:73], v[18:21], off offset:256
	s_and_saveexec_b64 s[22:23], s[2:3]
	s_cbranch_execz .LBB0_358
	v_lshl_add_u64 v[18:19], v[52:53], 2, s[12:13]
	s_waitcnt lgkmcnt(0)
	v_add_f32_e32 v16, v16, v17
	global_atomic_add_f32 v[18:19], v16, off

.LBB0_365:
	v_mov_b32_e32 v28, v176
	s_and_b32 s14, s21, 0x1e0
	v_add_u32_e32 v8, s1, v28
	s_and_b32 s15, s19, 0xffffffc0
	s_bitset1_b32 s14, 14
	s_sub_i32 s26, s15, 32
	v_lshlrev_b32_e32 v0, 4, v28
	v_ashrrev_i32_e32 v9, 5, v8
	v_and_b32_e32 v0, 0x1f0, v0
	v_mov_b32_e32 v10, s26
	v_mov_b32_e32 v11, s14
	v_cmp_gt_i32_e32 vcc, 32, v9
	v_lshl_add_u64 v[2:3], s[10:11], 0, v[0:1]
	v_lshl_add_u64 v[4:5], s[36:37], 0, v[0:1]
	v_cndmask_b32_e32 v6, v10, v11, vcc
	v_add_u32_e32 v12, v6, v9
	v_cndmask_b32_e32 v7, v3, v5, vcc
	v_cndmask_b32_e32 v6, v2, v4, vcc
	v_mad_i64_i32 v[18:19], s[26:27], v12, s22, v[6:7]
	v_add_u32_e32 v6, 0x200, v8
	v_ashrrev_i32_e32 v12, 5, v6
	v_cmp_gt_i32_e32 vcc, 32, v12
	v_add_u32_e32 v0, 0, v0
	s_or_b32 s15, s15, s17
	v_cndmask_b32_e32 v6, v10, v11, vcc
	v_add_u32_e32 v13, v6, v12
	v_cndmask_b32_e32 v7, v3, v5, vcc
	v_cndmask_b32_e32 v6, v2, v4, vcc
	v_mad_i64_i32 v[16:17], s[26:27], v13, s22, v[6:7]
	v_add_u32_e32 v6, 0x400, v8
	v_ashrrev_i32_e32 v13, 5, v6
	v_cmp_gt_i32_e32 vcc, 32, v13
	s_add_i32 s14, s14, s16
	s_nop 0
	v_cndmask_b32_e32 v6, v10, v11, vcc
	v_add_u32_e32 v14, v6, v13
	v_cndmask_b32_e32 v7, v3, v5, vcc
	v_cndmask_b32_e32 v6, v2, v4, vcc
	v_mad_i64_i32 v[20:21], s[26:27], v14, s22, v[6:7]
	v_add_u32_e32 v6, 0x600, v8
	v_ashrrev_i32_e32 v14, 5, v6
	v_cmp_gt_i32_e32 vcc, 32, v14
	s_nop 1
	v_cndmask_b32_e32 v6, v10, v11, vcc
	v_add_u32_e32 v15, v6, v14
	v_cndmask_b32_e32 v7, v3, v5, vcc
	v_cndmask_b32_e32 v6, v2, v4, vcc
	v_mad_i64_i32 v[22:23], s[26:27], v15, s22, v[6:7]
	v_add_u32_e32 v6, 0x800, v8
	v_ashrrev_i32_e32 v15, 5, v6
	v_cmp_gt_i32_e32 vcc, 32, v15
	s_nop 1
	v_cndmask_b32_e32 v6, v10, v11, vcc
	v_add_u32_e32 v24, v6, v15
	v_cndmask_b32_e32 v7, v3, v5, vcc
	v_cndmask_b32_e32 v6, v2, v4, vcc
	v_mad_i64_i32 v[24:25], s[26:27], v24, s22, v[6:7]
	v_add_u32_e32 v6, 0xa00, v8
	v_ashrrev_i32_e32 v29, 5, v6
	v_cmp_gt_i32_e32 vcc, 32, v29
	s_nop 1
	v_cndmask_b32_e32 v6, v10, v11, vcc
	v_add_u32_e32 v6, v6, v29
	v_cndmask_b32_e32 v3, v3, v5, vcc
	v_cndmask_b32_e32 v2, v2, v4, vcc
	v_mad_i64_i32 v[26:27], s[26:27], v6, s22, v[2:3]
	global_load_dwordx4 v[136:139], v[18:19], off
	global_load_dwordx4 v[140:143], v[16:17], off
	global_load_dwordx4 v[144:147], v[20:21], off
	global_load_dwordx4 v[148:151], v[22:23], off
	global_load_dwordx4 v[152:155], v[24:25], off
	global_load_dwordx4 v[156:159], v[26:27], off
	global_load_dwordx4 v[178:181], v[18:19], off offset:512
	global_load_dwordx4 v[182:185], v[16:17], off offset:512
	global_load_dwordx4 v[186:189], v[20:21], off offset:512
	global_load_dwordx4 v[190:193], v[22:23], off offset:512
	global_load_dwordx4 v[194:197], v[24:25], off offset:512
	global_load_dwordx4 v[198:201], v[26:27], off offset:512
	global_load_dwordx4 v[206:209], v[18:19], off offset:1024
	global_load_dwordx4 v[210:213], v[16:17], off offset:1024
	global_load_dwordx4 v[214:217], v[20:21], off offset:1024
	global_load_dwordx4 v[218:221], v[22:23], off offset:1024
	global_load_dwordx4 v[120:123], v[24:25], off offset:1024
	global_load_dwordx4 v[124:127], v[26:27], off offset:1024
	v_mov_b32_e32 v112, 0x1000
	v_mov_b32_e32 v113, 0
	v_lshl_add_u64 v[128:129], v[18:19], 0, v[112:113]
	v_lshl_add_u64 v[130:131], v[16:17], 0, v[112:113]
	v_lshl_add_u64 v[132:133], v[20:21], 0, v[112:113]
	v_lshl_add_u64 v[106:107], v[22:23], 0, v[112:113]
	v_lshl_add_u64 v[108:109], v[24:25], 0, v[112:113]
	v_lshl_add_u64 v[110:111], v[26:27], 0, v[112:113]
	v_mad_u64_u32 v[4:5], s[26:27], v9, s23, v[0:1]
	v_mad_u64_u32 v[6:7], s[26:27], v12, s23, v[0:1]
	v_mad_u64_u32 v[8:9], s[26:27], v13, s23, v[0:1]
	v_mad_u64_u32 v[10:11], s[26:27], v14, s23, v[0:1]
	v_mad_u64_u32 v[12:13], s[26:27], v15, s23, v[0:1]
	v_mad_u64_u32 v[14:15], s[26:27], v29, s23, v[0:1]
	s_barrier
	v_and_b32_e32 v0, 15, v28
	v_and_b32_e32 v2, -16, v28
	v_add_u32_e32 v2, 0, v2
	v_or_b32_e32 v5, s18, v0
	v_mad_u32_u24 v5, v5, s23, v2
	v_or_b32_e32 v3, s16, v0
	v_mad_u64_u32 v[2:3], s[26:27], v3, s23, v[2:3]
	v_ashrrev_i32_e32 v3, 2, v28
	v_and_b32_e32 v3, -4, v3
	v_or_b32_e32 v0, s14, v0
	s_waitcnt vmcnt(17)
	ds_write_b128 v4, v[136:139]
	s_waitcnt vmcnt(16)
	ds_write_b128 v6, v[140:143]
	s_waitcnt vmcnt(15)
	ds_write_b128 v8, v[144:147]
	s_waitcnt vmcnt(14)
	ds_write_b128 v10, v[148:151]
	s_waitcnt vmcnt(13)
	ds_write_b128 v12, v[152:155]
	s_waitcnt vmcnt(12)
	ds_write_b128 v14, v[156:159]
	s_waitcnt lgkmcnt(0)
	s_barrier
	global_load_dwordx4 v[136:139], v[18:19], off offset:1536
	global_load_dwordx4 v[140:143], v[16:17], off offset:1536
	global_load_dwordx4 v[144:147], v[20:21], off offset:1536
	global_load_dwordx4 v[148:151], v[22:23], off offset:1536
	global_load_dwordx4 v[152:155], v[24:25], off offset:1536
	global_load_dwordx4 v[156:159], v[26:27], off offset:1536
	ds_read_b128 v[54:57], v5
	ds_read_b128 v[58:61], v5 offset:64
	ds_read_b128 v[62:65], v2
	ds_read_b128 v[66:69], v2 offset:64
	s_waitcnt lgkmcnt(1)
	v_mfma_f32_16x16x32_f16 v[54:57], v[54:57], v[62:65], 0
	ds_read_b128 v[62:65], v5 offset:128
	ds_read_b128 v[70:73], v5 offset:192
	s_waitcnt lgkmcnt(2)
	v_mfma_f32_16x16x32_f16 v[54:57], v[58:61], v[66:69], v[54:57]
	ds_read_b128 v[58:61], v2 offset:128
	ds_read_b128 v[66:69], v2 offset:192
	s_waitcnt lgkmcnt(1)
	v_mfma_f32_16x16x32_f16 v[54:57], v[62:65], v[58:61], v[54:57]
	ds_read_b128 v[58:61], v5 offset:256
	ds_read_b128 v[62:65], v5 offset:320
	s_waitcnt lgkmcnt(2)
	v_mfma_f32_16x16x32_f16 v[54:57], v[70:73], v[66:69], v[54:57]
	ds_read_b128 v[66:69], v2 offset:256
	ds_read_b128 v[70:73], v2 offset:320
	ds_read_b128 v[74:77], v5 offset:384
	s_waitcnt lgkmcnt(2)
	v_mfma_f32_16x16x32_f16 v[54:57], v[58:61], v[66:69], v[54:57]
	ds_read_b128 v[58:61], v2 offset:384
	ds_read_b128 v[66:69], v2 offset:448
	ds_read_b128 v[78:81], v5 offset:448
	s_waitcnt lgkmcnt(0)
	s_barrier
	s_waitcnt vmcnt(17)
	ds_write_b128 v4, v[178:181]
	s_waitcnt vmcnt(16)
	ds_write_b128 v6, v[182:185]
	s_waitcnt vmcnt(15)
	ds_write_b128 v8, v[186:189]
	s_waitcnt vmcnt(14)
	ds_write_b128 v10, v[190:193]
	s_waitcnt vmcnt(13)
	ds_write_b128 v12, v[194:197]
	s_waitcnt vmcnt(12)
	ds_write_b128 v14, v[198:201]
	s_waitcnt lgkmcnt(0)
	s_barrier
	global_load_dwordx4 v[178:181], v[18:19], off offset:2048
	global_load_dwordx4 v[182:185], v[16:17], off offset:2048
	global_load_dwordx4 v[186:189], v[20:21], off offset:2048
	global_load_dwordx4 v[190:193], v[22:23], off offset:2048
	global_load_dwordx4 v[194:197], v[24:25], off offset:2048
	global_load_dwordx4 v[198:201], v[26:27], off offset:2048
	v_mfma_f32_16x16x32_f16 v[54:57], v[62:65], v[70:73], v[54:57]
	v_mfma_f32_16x16x32_f16 v[54:57], v[74:77], v[58:61], v[54:57]
	ds_read_b128 v[58:61], v5
	v_mfma_f32_16x16x32_f16 v[54:57], v[78:81], v[66:69], v[54:57]
	ds_read_b128 v[62:65], v5 offset:64
	ds_read_b128 v[66:69], v2
	ds_read_b128 v[70:73], v2 offset:64
	s_waitcnt lgkmcnt(1)
	v_mfma_f32_16x16x32_f16 v[54:57], v[58:61], v[66:69], v[54:57]
	ds_read_b128 v[58:61], v5 offset:128
	ds_read_b128 v[66:69], v5 offset:192
	s_waitcnt lgkmcnt(2)
	v_mfma_f32_16x16x32_f16 v[54:57], v[62:65], v[70:73], v[54:57]
	ds_read_b128 v[62:65], v2 offset:128
	ds_read_b128 v[70:73], v2 offset:192
	s_waitcnt lgkmcnt(1)
	v_mfma_f32_16x16x32_f16 v[54:57], v[58:61], v[62:65], v[54:57]
	ds_read_b128 v[58:61], v5 offset:256
	ds_read_b128 v[62:65], v5 offset:320
	s_waitcnt lgkmcnt(2)
	v_mfma_f32_16x16x32_f16 v[54:57], v[66:69], v[70:73], v[54:57]
	ds_read_b128 v[66:69], v2 offset:256
	ds_read_b128 v[70:73], v2 offset:320
	ds_read_b128 v[74:77], v5 offset:384
	s_waitcnt lgkmcnt(2)
	v_mfma_f32_16x16x32_f16 v[54:57], v[58:61], v[66:69], v[54:57]
	ds_read_b128 v[58:61], v2 offset:384
	ds_read_b128 v[66:69], v2 offset:448
	ds_read_b128 v[78:81], v5 offset:448
	s_waitcnt lgkmcnt(0)
	s_barrier
	s_waitcnt vmcnt(17)
	ds_write_b128 v4, v[206:209]
	s_waitcnt vmcnt(16)
	ds_write_b128 v6, v[210:213]
	s_waitcnt vmcnt(15)
	ds_write_b128 v8, v[214:217]
	s_waitcnt vmcnt(14)
	ds_write_b128 v10, v[218:221]
	s_waitcnt vmcnt(13)
	ds_write_b128 v12, v[120:123]
	s_waitcnt vmcnt(12)
	ds_write_b128 v14, v[124:127]
	s_waitcnt lgkmcnt(0)
	s_barrier
	global_load_dwordx4 v[206:209], v[18:19], off offset:2560
	global_load_dwordx4 v[210:213], v[16:17], off offset:2560
	global_load_dwordx4 v[214:217], v[20:21], off offset:2560
	global_load_dwordx4 v[218:221], v[22:23], off offset:2560
	global_load_dwordx4 v[120:123], v[24:25], off offset:2560
	global_load_dwordx4 v[124:127], v[26:27], off offset:2560
	v_mfma_f32_16x16x32_f16 v[54:57], v[62:65], v[70:73], v[54:57]
	v_mfma_f32_16x16x32_f16 v[54:57], v[74:77], v[58:61], v[54:57]
	ds_read_b128 v[58:61], v5
	v_mfma_f32_16x16x32_f16 v[54:57], v[78:81], v[66:69], v[54:57]
	ds_read_b128 v[62:65], v5 offset:64
	ds_read_b128 v[66:69], v2
	ds_read_b128 v[70:73], v2 offset:64
	s_waitcnt lgkmcnt(1)
	v_mfma_f32_16x16x32_f16 v[54:57], v[58:61], v[66:69], v[54:57]
	ds_read_b128 v[58:61], v5 offset:128
	ds_read_b128 v[66:69], v5 offset:192
	s_waitcnt lgkmcnt(2)
	v_mfma_f32_16x16x32_f16 v[54:57], v[62:65], v[70:73], v[54:57]
	ds_read_b128 v[62:65], v2 offset:128
	ds_read_b128 v[70:73], v2 offset:192
	s_waitcnt lgkmcnt(1)
	v_mfma_f32_16x16x32_f16 v[54:57], v[58:61], v[62:65], v[54:57]
	ds_read_b128 v[58:61], v5 offset:256
	ds_read_b128 v[62:65], v5 offset:320
	s_waitcnt lgkmcnt(2)
	v_mfma_f32_16x16x32_f16 v[54:57], v[66:69], v[70:73], v[54:57]
	ds_read_b128 v[66:69], v2 offset:256
	ds_read_b128 v[70:73], v2 offset:320
	ds_read_b128 v[74:77], v5 offset:384
	s_waitcnt lgkmcnt(2)
	v_mfma_f32_16x16x32_f16 v[54:57], v[58:61], v[66:69], v[54:57]
	ds_read_b128 v[58:61], v2 offset:384
	ds_read_b128 v[66:69], v2 offset:448
	ds_read_b128 v[78:81], v5 offset:448
	s_waitcnt lgkmcnt(0)
	s_barrier
	s_waitcnt vmcnt(17)
	ds_write_b128 v4, v[136:139]
	s_waitcnt vmcnt(16)
	ds_write_b128 v6, v[140:143]
	s_waitcnt vmcnt(15)
	ds_write_b128 v8, v[144:147]
	s_waitcnt vmcnt(14)
	ds_write_b128 v10, v[148:151]
	s_waitcnt vmcnt(13)
	ds_write_b128 v12, v[152:155]
	s_waitcnt vmcnt(12)
	ds_write_b128 v14, v[156:159]
	s_waitcnt lgkmcnt(0)
	s_barrier
	global_load_dwordx4 v[136:139], v[18:19], off offset:3072
	global_load_dwordx4 v[140:143], v[16:17], off offset:3072
	global_load_dwordx4 v[144:147], v[20:21], off offset:3072
	global_load_dwordx4 v[148:151], v[22:23], off offset:3072
	global_load_dwordx4 v[152:155], v[24:25], off offset:3072
	global_load_dwordx4 v[156:159], v[26:27], off offset:3072
	v_mfma_f32_16x16x32_f16 v[54:57], v[62:65], v[70:73], v[54:57]
	v_mfma_f32_16x16x32_f16 v[54:57], v[74:77], v[58:61], v[54:57]
	ds_read_b128 v[58:61], v5
	v_mfma_f32_16x16x32_f16 v[54:57], v[78:81], v[66:69], v[54:57]
	ds_read_b128 v[62:65], v5 offset:64
	ds_read_b128 v[66:69], v2
	ds_read_b128 v[70:73], v2 offset:64
	s_waitcnt lgkmcnt(1)
	v_mfma_f32_16x16x32_f16 v[54:57], v[58:61], v[66:69], v[54:57]
	ds_read_b128 v[58:61], v5 offset:128
	ds_read_b128 v[66:69], v5 offset:192
	s_waitcnt lgkmcnt(2)
	v_mfma_f32_16x16x32_f16 v[54:57], v[62:65], v[70:73], v[54:57]
	ds_read_b128 v[62:65], v2 offset:128
	ds_read_b128 v[70:73], v2 offset:192
	s_waitcnt lgkmcnt(1)
	v_mfma_f32_16x16x32_f16 v[54:57], v[58:61], v[62:65], v[54:57]
	ds_read_b128 v[58:61], v5 offset:256
	ds_read_b128 v[62:65], v5 offset:320
	s_waitcnt lgkmcnt(2)
	v_mfma_f32_16x16x32_f16 v[54:57], v[66:69], v[70:73], v[54:57]
	ds_read_b128 v[66:69], v2 offset:256
	ds_read_b128 v[70:73], v2 offset:320
	ds_read_b128 v[74:77], v5 offset:384
	s_waitcnt lgkmcnt(2)
	v_mfma_f32_16x16x32_f16 v[54:57], v[58:61], v[66:69], v[54:57]
	ds_read_b128 v[58:61], v2 offset:384
	ds_read_b128 v[66:69], v2 offset:448
	ds_read_b128 v[78:81], v5 offset:448
	s_waitcnt lgkmcnt(0)
	s_barrier
	s_waitcnt vmcnt(17)
	ds_write_b128 v4, v[178:181]
	s_waitcnt vmcnt(16)
	ds_write_b128 v6, v[182:185]
	s_waitcnt vmcnt(15)
	ds_write_b128 v8, v[186:189]
	s_waitcnt vmcnt(14)
	ds_write_b128 v10, v[190:193]
	s_waitcnt vmcnt(13)
	ds_write_b128 v12, v[194:197]
	s_waitcnt vmcnt(12)
	ds_write_b128 v14, v[198:201]
	s_waitcnt lgkmcnt(0)
	s_barrier
	global_load_dwordx4 v[178:181], v[18:19], off offset:3584
	global_load_dwordx4 v[182:185], v[16:17], off offset:3584
	global_load_dwordx4 v[186:189], v[20:21], off offset:3584
	global_load_dwordx4 v[190:193], v[22:23], off offset:3584
	global_load_dwordx4 v[194:197], v[24:25], off offset:3584
	global_load_dwordx4 v[198:201], v[26:27], off offset:3584
	v_mfma_f32_16x16x32_f16 v[54:57], v[62:65], v[70:73], v[54:57]
	v_mfma_f32_16x16x32_f16 v[54:57], v[74:77], v[58:61], v[54:57]
	ds_read_b128 v[58:61], v5
	v_mfma_f32_16x16x32_f16 v[54:57], v[78:81], v[66:69], v[54:57]
	ds_read_b128 v[62:65], v5 offset:64
	ds_read_b128 v[66:69], v2
	ds_read_b128 v[70:73], v2 offset:64
	s_waitcnt lgkmcnt(1)
	v_mfma_f32_16x16x32_f16 v[54:57], v[58:61], v[66:69], v[54:57]
	ds_read_b128 v[58:61], v5 offset:128
	ds_read_b128 v[66:69], v5 offset:192
	s_waitcnt lgkmcnt(2)
	v_mfma_f32_16x16x32_f16 v[54:57], v[62:65], v[70:73], v[54:57]
	ds_read_b128 v[62:65], v2 offset:128
	ds_read_b128 v[70:73], v2 offset:192
	s_waitcnt lgkmcnt(1)
	v_mfma_f32_16x16x32_f16 v[54:57], v[58:61], v[62:65], v[54:57]
	ds_read_b128 v[58:61], v5 offset:256
	ds_read_b128 v[62:65], v5 offset:320
	s_waitcnt lgkmcnt(2)
	v_mfma_f32_16x16x32_f16 v[54:57], v[66:69], v[70:73], v[54:57]
	ds_read_b128 v[66:69], v2 offset:256
	ds_read_b128 v[70:73], v2 offset:320
	ds_read_b128 v[74:77], v5 offset:384
	s_waitcnt lgkmcnt(2)
	v_mfma_f32_16x16x32_f16 v[54:57], v[58:61], v[66:69], v[54:57]
	ds_read_b128 v[58:61], v2 offset:384
	ds_read_b128 v[66:69], v2 offset:448
	ds_read_b128 v[78:81], v5 offset:448
	s_waitcnt lgkmcnt(0)
	s_barrier
	s_waitcnt vmcnt(17)
	ds_write_b128 v4, v[206:209]
	s_waitcnt vmcnt(16)
	ds_write_b128 v6, v[210:213]
	s_waitcnt vmcnt(15)
	ds_write_b128 v8, v[214:217]
	s_waitcnt vmcnt(14)
	ds_write_b128 v10, v[218:221]
	s_waitcnt vmcnt(13)
	ds_write_b128 v12, v[120:123]
	s_waitcnt vmcnt(12)
	ds_write_b128 v14, v[124:127]
	s_waitcnt lgkmcnt(0)
	s_barrier
	global_load_dwordx4 v[206:209], v[128:129], off
	global_load_dwordx4 v[210:213], v[130:131], off
	global_load_dwordx4 v[214:217], v[132:133], off
	global_load_dwordx4 v[218:221], v[106:107], off
	global_load_dwordx4 v[120:123], v[108:109], off
	global_load_dwordx4 v[124:127], v[110:111], off
	v_mfma_f32_16x16x32_f16 v[54:57], v[62:65], v[70:73], v[54:57]
	v_mfma_f32_16x16x32_f16 v[54:57], v[74:77], v[58:61], v[54:57]
	ds_read_b128 v[58:61], v5
	v_mfma_f32_16x16x32_f16 v[54:57], v[78:81], v[66:69], v[54:57]
	ds_read_b128 v[62:65], v2
	ds_read_b128 v[66:69], v2 offset:64
	ds_read_b128 v[70:73], v5 offset:64
	ds_read_b128 v[74:77], v2 offset:128
	ds_read_b128 v[78:81], v2 offset:192
	ds_read_b128 v[82:85], v5 offset:128
	ds_read_b128 v[86:89], v5 offset:192
	s_waitcnt lgkmcnt(6)
	v_mfma_f32_16x16x32_f16 v[54:57], v[58:61], v[62:65], v[54:57]
	ds_read_b128 v[58:61], v2 offset:256
	ds_read_b128 v[62:65], v2 offset:320
	ds_read_b128 v[90:93], v5 offset:256
	ds_read_b128 v[94:97], v5 offset:320
	s_waitcnt lgkmcnt(8)
	v_mfma_f32_16x16x32_f16 v[54:57], v[70:73], v[66:69], v[54:57]
	ds_read_b128 v[66:69], v2 offset:384
	ds_read_b128 v[70:73], v2 offset:448
	ds_read_b128 v[98:101], v5 offset:384
	ds_read_b128 v[102:105], v5 offset:448
	s_waitcnt lgkmcnt(0)
	s_barrier
	s_waitcnt vmcnt(17)
	ds_write_b128 v4, v[136:139]
	s_waitcnt vmcnt(16)
	ds_write_b128 v6, v[140:143]
	s_waitcnt vmcnt(15)
	ds_write_b128 v8, v[144:147]
	s_waitcnt vmcnt(14)
	ds_write_b128 v10, v[148:151]
	s_waitcnt vmcnt(13)
	ds_write_b128 v12, v[152:155]
	s_waitcnt vmcnt(12)
	ds_write_b128 v14, v[156:159]
	s_waitcnt lgkmcnt(0)
	s_barrier
	global_load_dwordx4 v[136:139], v[128:129], off offset:512
	global_load_dwordx4 v[140:143], v[130:131], off offset:512
	global_load_dwordx4 v[144:147], v[132:133], off offset:512
	global_load_dwordx4 v[148:151], v[106:107], off offset:512
	global_load_dwordx4 v[152:155], v[108:109], off offset:512
	global_load_dwordx4 v[156:159], v[110:111], off offset:512
	v_mfma_f32_16x16x32_f16 v[54:57], v[82:85], v[74:77], v[54:57]
	v_mfma_f32_16x16x32_f16 v[54:57], v[86:89], v[78:81], v[54:57]
	v_add_co_u32_e32 v78, vcc, s24, v18
	v_mfma_f32_16x16x32_f16 v[54:57], v[90:93], v[58:61], v[54:57]
	s_nop 0
	v_addc_co_u32_e32 v79, vcc, 0, v19, vcc
	v_add_co_u32_e32 v80, vcc, s24, v26
	v_mfma_f32_16x16x32_f16 v[54:57], v[94:97], v[62:65], v[54:57]
	s_nop 0
	v_addc_co_u32_e32 v81, vcc, 0, v27, vcc
	v_add_co_u32_e32 v82, vcc, s24, v24
	v_mfma_f32_16x16x32_f16 v[54:57], v[98:101], v[66:69], v[54:57]
	s_nop 0
	v_addc_co_u32_e32 v83, vcc, 0, v25, vcc
	ds_read_b128 v[24:27], v5
	v_mfma_f32_16x16x32_f16 v[54:57], v[102:105], v[70:73], v[54:57]
	ds_read_b128 v[58:61], v2
	ds_read_b128 v[62:65], v5 offset:64
	v_add_co_u32_e32 v84, vcc, s24, v22
	ds_read_b128 v[66:69], v2 offset:64
	s_nop 0
	v_addc_co_u32_e32 v85, vcc, 0, v23, vcc
	s_waitcnt lgkmcnt(2)
	v_mfma_f32_16x16x32_f16 v[22:25], v[24:27], v[58:61], v[54:57]
	s_nop 2
	ds_read_b128 v[54:57], v5 offset:128
	ds_read_b128 v[58:61], v2 offset:128
	ds_read_b128 v[70:73], v5 offset:192
	v_add_co_u32_e32 v86, vcc, s24, v20
	s_waitcnt lgkmcnt(3)
	v_mfma_f32_16x16x32_f16 v[22:25], v[62:65], v[66:69], v[22:25]
	v_addc_co_u32_e32 v87, vcc, 0, v21, vcc
	ds_read_b128 v[18:21], v2 offset:192
	s_waitcnt lgkmcnt(2)
	v_mfma_f32_16x16x32_f16 v[22:25], v[54:57], v[58:61], v[22:25]
	ds_read_b128 v[54:57], v2 offset:256
	ds_read_b128 v[58:61], v5 offset:256
	ds_read_b128 v[62:65], v5 offset:320
	v_add_co_u32_e32 v88, vcc, s24, v16
	s_waitcnt lgkmcnt(3)
	v_mfma_f32_16x16x32_f16 v[18:21], v[70:73], v[18:21], v[22:25]
	v_addc_co_u32_e32 v89, vcc, 0, v17, vcc
	s_nop 1
	ds_read_b128 v[22:25], v2 offset:320
	ds_read_b128 v[66:69], v5 offset:384
	s_waitcnt lgkmcnt(3)
	v_mfma_f32_16x16x32_f16 v[16:19], v[58:61], v[54:57], v[18:21]
	ds_read_b128 v[54:57], v2 offset:384
	ds_read_b128 v[58:61], v2 offset:448
	ds_read_b128 v[70:73], v5 offset:448
	s_waitcnt lgkmcnt(0)
	s_barrier
	v_mfma_f32_16x16x32_f16 v[16:19], v[62:65], v[22:25], v[16:19]
	s_waitcnt vmcnt(17)
	ds_write_b128 v4, v[178:181]
	s_waitcnt vmcnt(16)
	ds_write_b128 v6, v[182:185]
	s_waitcnt vmcnt(15)
	ds_write_b128 v8, v[186:189]
	s_waitcnt vmcnt(14)
	ds_write_b128 v10, v[190:193]
	s_waitcnt vmcnt(13)
	ds_write_b128 v12, v[194:197]
	s_waitcnt vmcnt(12)
	ds_write_b128 v14, v[198:201]
	s_waitcnt lgkmcnt(0)
	s_barrier
	global_load_dwordx4 v[178:181], v[128:129], off offset:1024
	global_load_dwordx4 v[182:185], v[130:131], off offset:1024
	global_load_dwordx4 v[186:189], v[132:133], off offset:1024
	global_load_dwordx4 v[190:193], v[106:107], off offset:1024
	global_load_dwordx4 v[194:197], v[108:109], off offset:1024
	global_load_dwordx4 v[198:201], v[110:111], off offset:1024
	ds_read_b128 v[46:49], v5
	v_mfma_f32_16x16x32_f16 v[16:19], v[66:69], v[54:57], v[16:19]
	v_cmp_gt_u32_e32 vcc, 16, v28
	v_mfma_f32_16x16x32_f16 v[16:19], v[70:73], v[58:61], v[16:19]
	ds_read_b128 v[50:53], v5 offset:64
	ds_read_b128 v[54:57], v2
	ds_read_b128 v[58:61], v2 offset:64
	s_waitcnt lgkmcnt(1)
	v_mfma_f32_16x16x32_f16 v[16:19], v[46:49], v[54:57], v[16:19]
	ds_read_b128 v[46:49], v5 offset:128
	ds_read_b128 v[54:57], v5 offset:192
	s_waitcnt lgkmcnt(2)
	v_mfma_f32_16x16x32_f16 v[16:19], v[50:53], v[58:61], v[16:19]
	ds_read_b128 v[50:53], v2 offset:128
	ds_read_b128 v[58:61], v2 offset:192
	s_waitcnt lgkmcnt(1)
	v_mfma_f32_16x16x32_f16 v[16:19], v[46:49], v[50:53], v[16:19]
	ds_read_b128 v[46:49], v5 offset:256
	ds_read_b128 v[50:53], v5 offset:320
	s_waitcnt lgkmcnt(2)
	v_mfma_f32_16x16x32_f16 v[16:19], v[54:57], v[58:61], v[16:19]
	ds_read_b128 v[54:57], v2 offset:256
	ds_read_b128 v[58:61], v2 offset:320
	ds_read_b128 v[62:65], v5 offset:384
	s_waitcnt lgkmcnt(2)
	v_mfma_f32_16x16x32_f16 v[16:19], v[46:49], v[54:57], v[16:19]
	ds_read_b128 v[46:49], v2 offset:384
	ds_read_b128 v[54:57], v2 offset:448
	ds_read_b128 v[66:69], v5 offset:448
	s_waitcnt lgkmcnt(0)
	s_barrier
	s_waitcnt vmcnt(17)
	ds_write_b128 v4, v[206:209]
	s_waitcnt vmcnt(16)
	ds_write_b128 v6, v[210:213]
	s_waitcnt vmcnt(15)
	ds_write_b128 v8, v[214:217]
	s_waitcnt vmcnt(14)
	ds_write_b128 v10, v[218:221]
	s_waitcnt vmcnt(13)
	ds_write_b128 v12, v[120:123]
	s_waitcnt vmcnt(12)
	ds_write_b128 v14, v[124:127]
	s_waitcnt lgkmcnt(0)
	s_barrier
	v_mfma_f32_16x16x32_f16 v[16:19], v[50:53], v[58:61], v[16:19]
	v_mfma_f32_16x16x32_f16 v[16:19], v[62:65], v[46:49], v[16:19]
	ds_read_b128 v[46:49], v5
	v_mfma_f32_16x16x32_f16 v[16:19], v[66:69], v[54:57], v[16:19]
	ds_read_b128 v[50:53], v5 offset:64
	ds_read_b128 v[54:57], v2
	ds_read_b128 v[58:61], v2 offset:64
	s_waitcnt lgkmcnt(1)
	v_mfma_f32_16x16x32_f16 v[16:19], v[46:49], v[54:57], v[16:19]
	ds_read_b128 v[46:49], v5 offset:128
	ds_read_b128 v[54:57], v5 offset:192
	s_waitcnt lgkmcnt(2)
	v_mfma_f32_16x16x32_f16 v[16:19], v[50:53], v[58:61], v[16:19]
	ds_read_b128 v[50:53], v2 offset:128
	ds_read_b128 v[58:61], v2 offset:192
	ds_read_b128 v[62:65], v5 offset:256
	s_waitcnt lgkmcnt(2)
	v_mfma_f32_16x16x32_f16 v[16:19], v[46:49], v[50:53], v[16:19]
	ds_read_b128 v[46:49], v2 offset:256
	ds_read_b128 v[50:53], v2 offset:320
	ds_read_b128 v[66:69], v5 offset:320
	s_waitcnt lgkmcnt(4)
	v_mfma_f32_16x16x32_f16 v[16:19], v[54:57], v[58:61], v[16:19]
	ds_read_b128 v[54:57], v2 offset:384
	ds_read_b128 v[58:61], v2 offset:448
	ds_read_b128 v[70:73], v5 offset:384
	ds_read_b128 v[74:77], v5 offset:448
	s_waitcnt lgkmcnt(0)
	s_barrier
	s_waitcnt vmcnt(11)
	ds_write_b128 v4, v[136:139]
	s_waitcnt vmcnt(10)
	ds_write_b128 v6, v[140:143]
	s_waitcnt vmcnt(9)
	ds_write_b128 v8, v[144:147]
	s_waitcnt vmcnt(8)
	ds_write_b128 v10, v[148:151]
	s_waitcnt vmcnt(7)
	ds_write_b128 v12, v[152:155]
	s_waitcnt vmcnt(6)
	ds_write_b128 v14, v[156:159]
	s_waitcnt lgkmcnt(0)
	s_barrier
	v_mfma_f32_16x16x32_f16 v[16:19], v[62:65], v[46:49], v[16:19]
	ds_read_b128 v[46:49], v5
	v_mfma_f32_16x16x32_f16 v[16:19], v[66:69], v[50:53], v[16:19]
	v_mfma_f32_16x16x32_f16 v[16:19], v[70:73], v[54:57], v[16:19]
	ds_read_b128 v[50:53], v2
	ds_read_b128 v[54:57], v5 offset:64
	v_mfma_f32_16x16x32_f16 v[16:19], v[74:77], v[58:61], v[16:19]
	ds_read_b128 v[58:61], v2 offset:64
	ds_read_b128 v[62:65], v5 offset:128
	s_waitcnt lgkmcnt(3)
	v_mfma_f32_16x16x32_f16 v[16:19], v[46:49], v[50:53], v[16:19]
	ds_read_b128 v[46:49], v2 offset:128
	ds_read_b128 v[50:53], v5 offset:192
	s_waitcnt lgkmcnt(3)
	v_mfma_f32_16x16x32_f16 v[16:19], v[54:57], v[58:61], v[16:19]
	ds_read_b128 v[54:57], v2 offset:192
	ds_read_b128 v[58:61], v5 offset:256
	s_waitcnt lgkmcnt(3)
	v_mfma_f32_16x16x32_f16 v[16:19], v[62:65], v[46:49], v[16:19]
	ds_read_b128 v[46:49], v2 offset:256
	ds_read_b128 v[62:65], v2 offset:320
	ds_read_b128 v[66:69], v5 offset:320
	s_waitcnt lgkmcnt(4)
	v_mfma_f32_16x16x32_f16 v[16:19], v[50:53], v[54:57], v[16:19]
	ds_read_b128 v[50:53], v2 offset:384
	ds_read_b128 v[54:57], v2 offset:448
	ds_read_b128 v[70:73], v5 offset:384
	ds_read_b128 v[74:77], v5 offset:448
	s_waitcnt lgkmcnt(0)
	s_barrier
	v_mfma_f32_16x16x32_f16 v[16:19], v[58:61], v[46:49], v[16:19]
	s_waitcnt vmcnt(5)
	ds_write_b128 v4, v[178:181]
	s_waitcnt vmcnt(4)
	ds_write_b128 v6, v[182:185]
	s_waitcnt vmcnt(3)
	ds_write_b128 v8, v[186:189]
	s_waitcnt vmcnt(2)
	ds_write_b128 v10, v[190:193]
	s_waitcnt vmcnt(1)
	ds_write_b128 v12, v[194:197]
	s_waitcnt vmcnt(0)
	ds_write_b128 v14, v[198:201]
	v_mfma_f32_16x16x32_f16 v[16:19], v[66:69], v[62:65], v[16:19]
	s_waitcnt lgkmcnt(0)
	s_barrier
	ds_read_b128 v[6:9], v5
	v_mfma_f32_16x16x32_f16 v[10:13], v[70:73], v[50:53], v[16:19]
	s_nop 3
	ds_read_b128 v[14:17], v2
	ds_read_b128 v[18:21], v5 offset:64
	ds_read_b128 v[22:25], v2 offset:64
	ds_read_b128 v[30:33], v5 offset:128
	v_add_u32_e32 v26, s15, v3
	v_mfma_f32_16x16x32_f16 v[10:13], v[74:77], v[54:57], v[10:13]
	v_lshlrev_b64 v[34:35], 10, v[0:1]
	v_ashrrev_i32_e32 v27, 31, v26
	v_lshl_add_u64 v[34:35], v[34:35], 0, v[26:27]
	s_waitcnt lgkmcnt(3)
	v_mfma_f32_16x16x32_f16 v[6:9], v[6:9], v[14:17], v[10:13]
	s_nop 2
	ds_read_b128 v[10:13], v2 offset:128
	ds_read_b128 v[14:17], v5 offset:192
	v_lshlrev_b64 v[26:27], 2, v[26:27]
	v_lshl_add_u64 v[36:37], v[34:35], 2, s[38:39]
	s_waitcnt lgkmcnt(3)
	v_mfma_f32_16x16x32_f16 v[6:9], v[18:21], v[22:25], v[6:9]
	ds_read_b128 v[18:21], v2 offset:192
	ds_read_b128 v[22:25], v5 offset:256
	s_waitcnt lgkmcnt(3)
	v_mfma_f32_16x16x32_f16 v[6:9], v[30:33], v[10:13], v[6:9]
	ds_read_b128 v[10:13], v2 offset:256
	ds_read_b128 v[30:33], v5 offset:320
	s_waitcnt lgkmcnt(3)
	v_mfma_f32_16x16x32_f16 v[6:9], v[14:17], v[18:21], v[6:9]
	ds_read_b128 v[14:17], v2 offset:320
	ds_read_b128 v[18:21], v5 offset:384
	s_waitcnt lgkmcnt(3)
	v_mfma_f32_16x16x32_f16 v[6:9], v[22:25], v[10:13], v[6:9]
	ds_read_b128 v[10:13], v2 offset:384
	v_lshl_add_u64 v[22:23], s[2:3], 0, v[26:27]
	s_waitcnt lgkmcnt(2)
	v_mfma_f32_16x16x32_f16 v[6:9], v[30:33], v[14:17], v[6:9]
	ds_read_b128 v[14:17], v2 offset:448
	ds_read_b128 v[2:5], v5 offset:448
	global_load_dwordx4 v[22:25], v[22:23], off
	s_waitcnt lgkmcnt(2)
	v_mfma_f32_16x16x32_f16 v[6:9], v[18:21], v[10:13], v[6:9]
	v_lshl_add_u64 v[242:243], s[100:101], 0, v[36:37]
	global_load_dwordx4 v[10:13], v[242:243], off
	v_lshl_add_u64 v[18:19], s[4:5], 0, v[26:27]
	s_waitcnt lgkmcnt(0)
	v_mfma_f32_16x16x32_f16 v[2:5], v[2:5], v[14:17], v[6:9]
	s_waitcnt vmcnt(1)
	s_nop 2
	v_pk_mul_f32 v[6:7], v[24:25], 0.5 op_sel_hi:[1,0]
	v_pk_mul_f32 v[8:9], v[22:23], 0.5 op_sel_hi:[1,0]
	s_waitcnt vmcnt(0)
	s_nop 0
	v_pk_fma_f32 v[6:7], v[4:5], v[6:7], v[12:13]
	v_pk_fma_f32 v[4:5], v[2:3], v[8:9], v[10:11]
	global_store_dwordx4 v[36:37], v[4:7], off
	global_load_dwordx4 v[8:11], v[18:19], off
	v_mul_f32_e32 v2, v5, v5
	v_mul_f32_e32 v3, v7, v7
	v_fmac_f32_e32 v2, v4, v4
	v_fmac_f32_e32 v3, v6, v6
	v_add_f32_e32 v2, v2, v3
	ds_bpermute_b32 v3, v134, v2
	v_lshl_add_u64 v[12:13], v[34:35], 1, s[42:43]
	s_waitcnt lgkmcnt(0)
	v_add_f32_e32 v2, v2, v3
	ds_bpermute_b32 v3, v135, v2
	s_waitcnt vmcnt(0)
	v_pk_mul_f32 v[6:7], v[10:11], v[6:7]
	v_pk_mul_f32 v[4:5], v[8:9], v[4:5]
	s_nop 0
	v_cvt_pk_f16_f32 v4, v4, v5
	v_cvt_pk_f16_f32 v5, v6, v7
	global_store_dwordx2 v[12:13], v[4:5], off
	s_and_saveexec_b64 s[14:15], vcc
	s_cbranch_execz .LBB0_364
	v_lshlrev_b32_e32 v0, 2, v0
	s_waitcnt lgkmcnt(0)
	v_add_f32_e32 v2, v2, v3
	global_atomic_add_f32 v0, v2, s[12:13]
	s_branch .LBB0_364

	.amdhsa_kernel _Z14fwd_megakernel4Args
		.amdhsa_group_segment_fixed_size 0
		.amdhsa_private_segment_fixed_size 0
		.amdhsa_kernarg_size 472
		.amdhsa_user_sgpr_count 2
		.amdhsa_user_sgpr_dispatch_ptr 0
		.amdhsa_user_sgpr_queue_ptr 0
		.amdhsa_user_sgpr_kernarg_segment_ptr 1
		.amdhsa_user_sgpr_dispatch_id 0
		.amdhsa_user_sgpr_kernarg_preload_length 0
		.amdhsa_user_sgpr_kernarg_preload_offset 0
		.amdhsa_user_sgpr_private_segment_size 0
		.amdhsa_uses_dynamic_stack 0
		.amdhsa_enable_private_segment 0
		.amdhsa_system_sgpr_workgroup_id_x 1
		.amdhsa_system_sgpr_workgroup_id_y 0
		.amdhsa_system_sgpr_workgroup_id_z 0
		.amdhsa_system_sgpr_workgroup_info 0
		.amdhsa_system_vgpr_workitem_id 2
		.amdhsa_next_free_vgpr 248
		.amdhsa_next_free_sgpr 102
		.amdhsa_accum_offset 244
		.amdhsa_reserve_vcc 1
		.amdhsa_float_round_mode_32 0
		.amdhsa_float_round_mode_16_64 0
		.amdhsa_float_denorm_mode_32 3
		.amdhsa_float_denorm_mode_16_64 3
		.amdhsa_dx10_clamp 1
		.amdhsa_ieee_mode 1
		.amdhsa_fp16_overflow 0
		.amdhsa_tg_split 0
		.amdhsa_exception_fp_ieee_invalid_op 0
		.amdhsa_exception_fp_denorm_src 0
		.amdhsa_exception_fp_ieee_div_zero 0
		.amdhsa_exception_fp_ieee_overflow 0
		.amdhsa_exception_fp_ieee_underflow 0
		.amdhsa_exception_fp_ieee_inexact 0
		.amdhsa_exception_int_div_zero 0
	.end_amdhsa_kernel

amdhsa.kernels:
  - .agpr_count:     0
    .args:
      - .offset:         0
        .size:           216
        .value_kind:     by_value
      - .offset:         216
        .size:           4
        .value_kind:     hidden_block_count_x
      - .offset:         220
        .size:           4
        .value_kind:     hidden_block_count_y
      - .offset:         224
        .size:           4
        .value_kind:     hidden_block_count_z
      - .offset:         228
        .size:           2
        .value_kind:     hidden_group_size_x
      - .offset:         230
        .size:           2
        .value_kind:     hidden_group_size_y
      - .offset:         232
        .size:           2
        .value_kind:     hidden_group_size_z
      - .offset:         234
        .size:           2
        .value_kind:     hidden_remainder_x
      - .offset:         236
        .size:           2
        .value_kind:     hidden_remainder_y
      - .offset:         238
        .size:           2
        .value_kind:     hidden_remainder_z
      - .offset:         256
        .size:           8
        .value_kind:     hidden_global_offset_x
      - .offset:         264
        .size:           8
        .value_kind:     hidden_global_offset_y
      - .offset:         272
        .size:           8
        .value_kind:     hidden_global_offset_z
      - .offset:         280
        .size:           2
        .value_kind:     hidden_grid_dims
      - .offset:         304
        .size:           8
        .value_kind:     hidden_multigrid_sync_arg
      - .offset:         336
        .size:           4
        .value_kind:     hidden_dynamic_lds_size
    .group_segment_fixed_size: 0
    .kernarg_segment_align: 8
    .kernarg_segment_size: 472
    .language:       OpenCL C
    .language_version:
      - 2
      - 0
    .max_flat_workgroup_size: 512
    .name:           _Z14fwd_megakernel4Args
    .private_segment_fixed_size: 0
    .sgpr_count:     108
    .sgpr_spill_count: 43
    .symbol:         _Z14fwd_megakernel4Args.kd
    .uniform_work_group_size: 1
    .uses_dynamic_stack: false
    .vgpr_count:     248
    .vgpr_spill_count: 0
    .wavefront_size: 64
